# w_ff2 weight-conversion loops (phase C and the FFN-up GEMM idle tail): 32 loads per item back to back with one wait, instead of 13 vmcnt(0) round trips
# speedup vs baseline: 1.0047x; 1.0033x over previous
; __device__ __forceinline__ void transpose_item(const float* W, int K, int N, int NP, bf16* WT, LAS float* scr, int item, int lane, const LAS float* tab, long long* bias, int ldb, const float* kscale = nullptr) {
;     const int nblk = NP / 32, kb = item / nblk, nb = item - kb * nblk, k0 = 64 * kb, n0 = 32 * nb;
;     const int n = n0 + (lane & 31); const bool okn = n < N;
;     float wv_[32];
;     const float* wp = W + (size_t)(k0 + (lane >> 5)) * N + (okn ? n : 0);
; #pragma unroll
;     for (int i = 0; i < 32; ++i) wv_[i] = wp[(size_t)(2 * i) * N];
; #pragma unroll
;     for (int i = 0; i < 32; ++i) { if (!okn) wv_[i] = 0.f; if (kscale != nullptr) wv_[i] *= kscale[k0 + 2 * i + (lane >> 5)]; scr[(2 * i + (lane >> 5)) * 33 + (lane & 31)] = wv_[i]; }
.LBB0_132:
	s_ashr_i32 s2, s12, 31
	s_lshr_b32 s2, s2, 26
	s_add_i32 s2, s12, s2
	s_and_b32 s6, s2, 0xffffffc0
	s_lshl_b32 s2, s2, 5
	s_and_b32 s2, s2, 0xfffff800
	s_sub_i32 s14, s13, s2
	v_add_u32_e32 v14, s14, v10
	v_or_b32_e32 v12, s6, v45
	v_cmp_gt_i32_e32 vcc, s56, v14
	v_ashrrev_i32_e32 v13, 31, v12
	v_lshlrev_b64 v[12:13], 13, v[12:13]
	v_cndmask_b32_e32 v14, 0, v14, vcc
	v_lshl_add_u64 v[12:13], s[4:5], 0, v[12:13]
	v_ashrrev_i32_e32 v15, 31, v14
	v_lshl_add_u64 v[40:41], v[14:15], 2, v[12:13]
	v_add_co_u32_e64 v12, s[2:3], s46, v40
	global_load_dword v39, v[40:41], off
	s_nop 0
	v_addc_co_u32_e64 v13, s[2:3], 0, v41, s[2:3]
	global_load_dword v42, v[12:13], off
	v_add_co_u32_e64 v12, s[2:3], s41, v40
	s_ashr_i32 s7, s6, 31
	s_nop 0
	v_addc_co_u32_e64 v13, s[2:3], 0, v41, s[2:3]
	global_load_dword v43, v[12:13], off
	v_add_co_u32_e64 v12, s[2:3], s18, v40
	s_add_i32 s12, s12, s76
	s_nop 0
	v_addc_co_u32_e64 v13, s[2:3], 0, v41, s[2:3]
	global_load_dword v47, v[12:13], off
	v_add_co_u32_e64 v12, s[2:3], s92, v40
	v_add_u32_e32 v10, s53, v10
	s_nop 0
	v_addc_co_u32_e64 v13, s[2:3], 0, v41, s[2:3]
	global_load_dword v48, v[12:13], off
	v_add_co_u32_e64 v12, s[2:3], s60, v40
	s_cmpk_lt_i32 s12, 0x2000
	s_nop 0
	v_addc_co_u32_e64 v13, s[2:3], 0, v41, s[2:3]
	global_load_dword v49, v[12:13], off
	v_add_co_u32_e64 v12, s[2:3], s61, v40
	s_nop 1
	v_addc_co_u32_e64 v13, s[2:3], 0, v41, s[2:3]
	global_load_dword v35, v[12:13], off
	v_add_co_u32_e64 v12, s[2:3], s15, v40
	s_nop 1
	v_addc_co_u32_e64 v13, s[2:3], 0, v41, s[2:3]
	global_load_dword v36, v[12:13], off
	v_add_co_u32_e64 v12, s[2:3], s78, v40
	s_nop 1
	v_addc_co_u32_e64 v13, s[2:3], 0, v41, s[2:3]
	global_load_dword v37, v[12:13], off
	v_add_co_u32_e64 v12, s[2:3], s16, v40
	s_nop 1
	v_addc_co_u32_e64 v13, s[2:3], 0, v41, s[2:3]
	global_load_dword v38, v[12:13], off
	v_add_co_u32_e64 v12, s[2:3], s17, v40
	s_nop 1
	v_addc_co_u32_e64 v13, s[2:3], 0, v41, s[2:3]
	global_load_dword v30, v[12:13], off
	v_add_co_u32_e64 v12, s[2:3], s19, v40
	s_nop 1
	v_addc_co_u32_e64 v13, s[2:3], 0, v41, s[2:3]
	global_load_dword v31, v[12:13], off
	v_add_co_u32_e64 v12, s[2:3], s49, v40
	s_nop 1
	v_addc_co_u32_e64 v13, s[2:3], 0, v41, s[2:3]
	global_load_dword v32, v[12:13], off
	v_add_co_u32_e64 v12, s[2:3], s22, v40
	s_nop 1
	v_addc_co_u32_e64 v13, s[2:3], 0, v41, s[2:3]
	global_load_dword v34, v[12:13], off
	v_add_co_u32_e64 v12, s[2:3], s23, v40
	s_nop 1
	v_addc_co_u32_e64 v13, s[2:3], 0, v41, s[2:3]
	global_load_dword v26, v[12:13], off
	v_add_co_u32_e64 v12, s[2:3], s39, v40
	s_nop 1
	v_addc_co_u32_e64 v13, s[2:3], 0, v41, s[2:3]
	global_load_dword v27, v[12:13], off
	v_add_co_u32_e64 v12, s[2:3], s79, v40
	s_nop 1
	v_addc_co_u32_e64 v13, s[2:3], 0, v41, s[2:3]
	global_load_dword v28, v[12:13], off
	v_add_co_u32_e64 v12, s[2:3], s72, v40
	s_nop 1
	v_addc_co_u32_e64 v13, s[2:3], 0, v41, s[2:3]
	global_load_dword v29, v[12:13], off
	v_add_co_u32_e64 v12, s[2:3], s8, v40
	s_nop 1
	v_addc_co_u32_e64 v13, s[2:3], 0, v41, s[2:3]
	global_load_dword v22, v[12:13], off
	v_add_co_u32_e64 v12, s[2:3], s73, v40
	s_nop 1
	v_addc_co_u32_e64 v13, s[2:3], 0, v41, s[2:3]
	global_load_dword v23, v[12:13], off
	v_add_co_u32_e64 v12, s[2:3], s0, v40
	s_nop 1
	v_addc_co_u32_e64 v13, s[2:3], 0, v41, s[2:3]
	global_load_dword v24, v[12:13], off
	v_add_co_u32_e64 v12, s[2:3], s9, v40
	s_nop 1
	v_addc_co_u32_e64 v13, s[2:3], 0, v41, s[2:3]
	global_load_dword v25, v[12:13], off
	v_add_co_u32_e64 v12, s[2:3], s10, v40
	s_nop 1
	v_addc_co_u32_e64 v13, s[2:3], 0, v41, s[2:3]
	global_load_dword v18, v[12:13], off
	v_add_co_u32_e64 v12, s[2:3], s11, v40
	s_nop 1
	v_addc_co_u32_e64 v13, s[2:3], 0, v41, s[2:3]
	global_load_dword v19, v[12:13], off
	v_add_co_u32_e64 v12, s[2:3], s40, v40
	s_nop 1
	v_addc_co_u32_e64 v13, s[2:3], 0, v41, s[2:3]
	global_load_dword v20, v[12:13], off
	v_add_co_u32_e64 v12, s[2:3], s90, v40
	s_nop 1
	v_addc_co_u32_e64 v13, s[2:3], 0, v41, s[2:3]
	global_load_dword v21, v[12:13], off
	v_add_co_u32_e64 v12, s[2:3], s91, v40
	s_nop 1
	v_addc_co_u32_e64 v13, s[2:3], 0, v41, s[2:3]
	global_load_dword v14, v[12:13], off
	v_add_co_u32_e64 v12, s[2:3], s31, v40
	s_nop 1
	v_addc_co_u32_e64 v13, s[2:3], 0, v41, s[2:3]
	global_load_dword v15, v[12:13], off
	v_add_co_u32_e64 v12, s[2:3], s96, v40
	s_nop 1
	v_addc_co_u32_e64 v13, s[2:3], 0, v41, s[2:3]
	global_load_dword v16, v[12:13], off
	v_add_co_u32_e64 v12, s[2:3], s25, v40
	s_nop 1
	v_addc_co_u32_e64 v13, s[2:3], 0, v41, s[2:3]
	global_load_dword v17, v[12:13], off
	v_add_co_u32_e64 v12, s[2:3], s82, v40
	s_nop 1
	v_addc_co_u32_e64 v13, s[2:3], 0, v41, s[2:3]
	v_add_co_u32_e64 v40, s[2:3], s83, v40
	global_load_dword v12, v[12:13], off
	s_nop 0
	v_addc_co_u32_e64 v41, s[2:3], 0, v41, s[2:3]
	global_load_dword v13, v[40:41], off
	s_waitcnt vmcnt(0)
; #define LAS __attribute__((address_space(3)))
; #define LDS_WAIT() asm volatile("s_waitcnt lgkmcnt(0)" ::: "memory")
; __device__ __forceinline__ unsigned pk2(float lo, float hi) { return pg8::pkbf(lo, hi); }
; __device__ __forceinline__ void transpose_item(const float* W, int K, int N, int NP, bf16* WT, LAS float* scr, int item, int lane, const LAS float* tab, long long* bias, int ldb, const float* kscale = nullptr) {
;     ...
;     for (int i = 0; i < 32; ++i) { if (!okn) wv_[i] = 0.f; if (kscale != nullptr) wv_[i] *= kscale[k0 + 2 * i + (lane >> 5)]; scr[(2 * i + (lane >> 5)) * 33 + (lane & 31)] = wv_[i]; }
;     if (tab != nullptr) {
;         const LAS float* tp = tab + k0 + (lane >> 5);
; #pragma unroll
;         for (int bp = 0; bp < 5; ++bp) { float s = 0.f;
; #pragma unroll
;             for (int i = 0; i < 32; ++i) s += tp[bp * 2048 + 2 * i] * wv_[i];
;             s += __shfl_xor(s, 32);
;             if (lane < 32) atomicAdd((unsigned long long*)(bias + (size_t)bp * ldb + n), (unsigned long long)(long long)(s * 4294967296.f)); }
;     }
;     LDS_WAIT(); asm volatile("" ::: "memory");
;     const int c = lane & 7;
; #pragma unroll
;     for (int j = 0; j < 4; ++j) { const int nn = (lane >> 3) + 8 * j; const LAS float* s = scr + (8 * c) * 33 + nn;
;         v4u o; o.x = pk2(s[0 * 33], s[1 * 33]); o.y = pk2(s[2 * 33], s[3 * 33]); o.z = pk2(s[4 * 33], s[5 * 33]); o.w = pk2(s[6 * 33], s[7 * 33]);
;         *(v4u*)(WT + (size_t)(n0 + nn) * K + k0 + 8 * c) = o; }
;     LDS_WAIT(); asm volatile("" ::: "memory");
	v_cndmask_b32_e32 v39, 0, v39, vcc
	v_cndmask_b32_e32 v35, 0, v35, vcc
	v_cndmask_b32_e32 v36, 0, v36, vcc
	v_cndmask_b32_e32 v30, 0, v30, vcc
	v_cndmask_b32_e32 v31, 0, v31, vcc
	v_cndmask_b32_e32 v26, 0, v26, vcc
	v_cndmask_b32_e32 v27, 0, v27, vcc
	v_cndmask_b32_e32 v22, 0, v22, vcc
	v_cndmask_b32_e32 v23, 0, v23, vcc
	v_cndmask_b32_e32 v18, 0, v18, vcc
	v_cndmask_b32_e32 v19, 0, v19, vcc
	v_cndmask_b32_e32 v14, 0, v14, vcc
	v_cndmask_b32_e32 v15, 0, v15, vcc
	v_add_u32_e32 v41, 0x400, v11
	ds_write2_b32 v41, v35, v36 offset0:140 offset1:206
	v_cndmask_b32_e32 v35, 0, v37, vcc
	v_add_u32_e32 v37, 0x800, v11
	ds_write2_b32 v37, v30, v31 offset0:148 offset1:214
	v_cndmask_b32_e32 v30, 0, v32, vcc
	v_add_u32_e32 v32, 0xc00, v11
	ds_write2_b32 v32, v26, v27 offset0:156 offset1:222
	v_cndmask_b32_e32 v26, 0, v28, vcc
	v_add_u32_e32 v28, 0x1000, v11
	v_cndmask_b32_e32 v40, 0, v42, vcc
	ds_write2_b32 v28, v22, v23 offset0:164 offset1:230
	v_cndmask_b32_e32 v22, 0, v24, vcc
	v_add_u32_e32 v24, 0x1400, v11
	ds_write2_b32 v11, v39, v40 offset1:66
	v_cndmask_b32_e32 v39, 0, v43, vcc
	v_cndmask_b32_e32 v40, 0, v47, vcc
	ds_write2_b32 v24, v18, v19 offset0:172 offset1:238
	v_cndmask_b32_e32 v18, 0, v20, vcc
	v_add_u32_e32 v20, 0x1800, v11
	ds_write2_b32 v11, v39, v40 offset0:132 offset1:198
	v_cndmask_b32_e32 v39, 0, v48, vcc
	v_cndmask_b32_e32 v40, 0, v49, vcc
	v_cndmask_b32_e32 v36, 0, v38, vcc
	v_cndmask_b32_e32 v31, 0, v34, vcc
	v_cndmask_b32_e32 v27, 0, v29, vcc
	v_cndmask_b32_e32 v23, 0, v25, vcc
	v_cndmask_b32_e32 v19, 0, v21, vcc
	ds_write2_b32 v20, v14, v15 offset0:180 offset1:246
	ds_write2_b32 v41, v39, v40 offset0:8 offset1:74
	ds_write2_b32 v37, v35, v36 offset0:16 offset1:82
	ds_write2_b32 v32, v30, v31 offset0:24 offset1:90
	ds_write2_b32 v28, v26, v27 offset0:32 offset1:98
	ds_write2_b32 v24, v22, v23 offset0:40 offset1:106
	ds_write2_b32 v20, v18, v19 offset0:48 offset1:114
	v_add_u32_e32 v32, s14, v9
	v_add_u32_e32 v36, 0x32000, v32
	v_ashrrev_i32_e32 v37, 31, v36
	v_lshlrev_b64 v[36:37], 14, v[36:37]
	v_add_u32_e32 v9, s53, v9
	s_waitcnt vmcnt(3)
	v_cndmask_b32_e32 v14, 0, v16, vcc
	v_add_u32_e32 v16, 0x1c00, v11
	s_waitcnt vmcnt(2)
	v_cndmask_b32_e32 v15, 0, v17, vcc
	ds_write2_b32 v16, v14, v15 offset0:56 offset1:122
	s_waitcnt vmcnt(1)
	v_cndmask_b32_e32 v12, 0, v12, vcc
	s_waitcnt vmcnt(0)
	v_cndmask_b32_e32 v13, 0, v13, vcc
	ds_write2_b32 v16, v12, v13 offset0:188 offset1:254
	s_waitcnt lgkmcnt(0)
	ds_read2_b32 v[18:19], v3 offset0:33 offset1:41
	ds_read2_b32 v[20:21], v3 offset1:8
	ds_read2_b32 v[22:23], v3 offset0:66 offset1:74
	ds_read2_b32 v[24:25], v3 offset0:99 offset1:107
	ds_read2_b32 v[26:27], v3 offset0:132 offset1:140
	ds_read2_b32 v[28:29], v3 offset0:165 offset1:173
	ds_read2_b32 v[30:31], v3 offset0:198 offset1:206
	ds_read2_b32 v[34:35], v3 offset0:231 offset1:239
	v_lshl_add_u64 v[16:17], s[6:7], 1, v[4:5]
	s_waitcnt lgkmcnt(6)
	v_cvt_pk_bf16_f32 v12, v20, v18
	s_waitcnt lgkmcnt(4)
	v_cvt_pk_bf16_f32 v13, v22, v24
	s_waitcnt lgkmcnt(2)
	v_cvt_pk_bf16_f32 v14, v26, v28
	s_waitcnt lgkmcnt(0)
	v_cvt_pk_bf16_f32 v15, v30, v34
	v_lshl_add_u64 v[36:37], v[16:17], 0, v[36:37]
	v_add_u32_e32 v18, 0x32008, v32
	global_store_dwordx4 v[36:37], v[12:15], off
	v_add_u32_e32 v36, 0x32010, v32
	v_ashrrev_i32_e32 v37, 31, v36
	v_cvt_pk_bf16_f32 v12, v21, v19
	v_ashrrev_i32_e32 v19, 31, v18
	v_lshlrev_b64 v[18:19], 14, v[18:19]
	v_cvt_pk_bf16_f32 v13, v23, v25
	v_cvt_pk_bf16_f32 v14, v27, v29
	v_cvt_pk_bf16_f32 v15, v31, v35
	v_lshl_add_u64 v[18:19], v[16:17], 0, v[18:19]
	global_store_dwordx4 v[18:19], v[12:15], off
	ds_read2_b32 v[18:19], v3 offset0:49 offset1:57
	ds_read2_b32 v[20:21], v3 offset0:16 offset1:24
	ds_read2_b32 v[22:23], v3 offset0:82 offset1:90
	ds_read2_b32 v[24:25], v3 offset0:115 offset1:123
	ds_read2_b32 v[26:27], v3 offset0:148 offset1:156
	ds_read2_b32 v[28:29], v3 offset0:181 offset1:189
	ds_read2_b32 v[30:31], v3 offset0:214 offset1:222
	ds_read2_b32 v[34:35], v3 offset0:247 offset1:255
	v_lshlrev_b64 v[36:37], 14, v[36:37]
	s_waitcnt lgkmcnt(6)
	v_cvt_pk_bf16_f32 v12, v20, v18
	s_waitcnt lgkmcnt(4)
	v_cvt_pk_bf16_f32 v13, v22, v24
	s_waitcnt lgkmcnt(2)
	v_cvt_pk_bf16_f32 v14, v26, v28
	s_waitcnt lgkmcnt(0)
	v_cvt_pk_bf16_f32 v15, v30, v34
	v_lshl_add_u64 v[36:37], v[16:17], 0, v[36:37]
	v_add_u32_e32 v18, 0x32018, v32
	global_store_dwordx4 v[36:37], v[12:15], off
	s_nop 1
	v_cvt_pk_bf16_f32 v12, v21, v19
	v_ashrrev_i32_e32 v19, 31, v18
	v_lshlrev_b64 v[18:19], 14, v[18:19]
	v_cvt_pk_bf16_f32 v13, v23, v25
	v_cvt_pk_bf16_f32 v14, v27, v29
	v_cvt_pk_bf16_f32 v15, v31, v35
	v_lshl_add_u64 v[16:17], v[16:17], 0, v[18:19]
	global_store_dwordx4 v[16:17], v[12:15], off
	s_waitcnt lgkmcnt(0)
	s_cbranch_scc1 .LBB0_132

; __device__ __forceinline__ void transpose_item(const float* W, int K, int N, int NP, bf16* WT, LAS float* scr, int item, int lane, const LAS float* tab, long long* bias, int ldb, const float* kscale = nullptr) {
;     const int nblk = NP / 32, kb = item / nblk, nb = item - kb * nblk, k0 = 64 * kb, n0 = 32 * nb;
;     const int n = n0 + (lane & 31); const bool okn = n < N;
;     float wv_[32];
;     const float* wp = W + (size_t)(k0 + (lane >> 5)) * N + (okn ? n : 0);
; #pragma unroll
;     for (int i = 0; i < 32; ++i) wv_[i] = wp[(size_t)(2 * i) * N];
; #pragma unroll
;     for (int i = 0; i < 32; ++i) { if (!okn) wv_[i] = 0.f; if (kscale != nullptr) wv_[i] *= kscale[k0 + 2 * i + (lane >> 5)]; scr[(2 * i + (lane >> 5)) * 33 + (lane & 31)] = wv_[i]; }
.LBB0_1368:
	s_ashr_i32 s4, s2, 31
	s_lshr_b32 s4, s4, 26
	s_add_i32 s4, s2, s4
	s_and_b32 s8, s4, 0xffffffc0
	s_lshl_b32 s4, s4, 5
	s_and_b32 s4, s4, 0xfffff800
	s_sub_i32 s10, s3, s4
	v_add_u32_e32 v10, s10, v8
	v_or_b32_e32 v6, s8, v1
	v_cmp_gt_i32_e32 vcc, s56, v10
	v_ashrrev_i32_e32 v7, 31, v6
	v_lshlrev_b64 v[6:7], 13, v[6:7]
	v_cndmask_b32_e32 v10, 0, v10, vcc
	v_lshl_add_u64 v[6:7], s[6:7], 0, v[6:7]
	v_ashrrev_i32_e32 v11, 31, v10
	v_lshl_add_u64 v[36:37], v[10:11], 2, v[6:7]
	v_add_co_u32_e64 v6, s[4:5], s43, v36
	global_load_dword v35, v[36:37], off
	s_nop 0
	v_addc_co_u32_e64 v7, s[4:5], 0, v37, s[4:5]
	global_load_dword v38, v[6:7], off
	v_add_co_u32_e64 v6, s[4:5], s11, v36
	s_ashr_i32 s9, s8, 31
	s_nop 0
	v_addc_co_u32_e64 v7, s[4:5], 0, v37, s[4:5]
	global_load_dword v39, v[6:7], off
	v_add_co_u32_e64 v6, s[4:5], s18, v36
	s_add_i32 s2, s2, s24
	s_nop 0
	v_addc_co_u32_e64 v7, s[4:5], 0, v37, s[4:5]
	global_load_dword v40, v[6:7], off
	v_add_co_u32_e64 v6, s[4:5], s92, v36
	v_add_u32_e32 v8, s38, v8
	s_nop 0
	v_addc_co_u32_e64 v7, s[4:5], 0, v37, s[4:5]
	global_load_dword v41, v[6:7], off
	v_add_co_u32_e64 v6, s[4:5], s12, v36
	s_cmpk_lt_i32 s2, 0x1900
	s_nop 0
	v_addc_co_u32_e64 v7, s[4:5], 0, v37, s[4:5]
	global_load_dword v42, v[6:7], off
	v_add_co_u32_e64 v6, s[4:5], s13, v36
	s_nop 1
	v_addc_co_u32_e64 v7, s[4:5], 0, v37, s[4:5]
	global_load_dword v30, v[6:7], off
	v_add_co_u32_e64 v6, s[4:5], s14, v36
	s_nop 1
	v_addc_co_u32_e64 v7, s[4:5], 0, v37, s[4:5]
	global_load_dword v31, v[6:7], off
	v_add_co_u32_e64 v6, s[4:5], s78, v36
	s_nop 1
	v_addc_co_u32_e64 v7, s[4:5], 0, v37, s[4:5]
	global_load_dword v32, v[6:7], off
	v_add_co_u32_e64 v6, s[4:5], s15, v36
	s_nop 1
	v_addc_co_u32_e64 v7, s[4:5], 0, v37, s[4:5]
	global_load_dword v34, v[6:7], off
	v_add_co_u32_e64 v6, s[4:5], s16, v36
	s_nop 1
	v_addc_co_u32_e64 v7, s[4:5], 0, v37, s[4:5]
	global_load_dword v26, v[6:7], off
	v_add_co_u32_e64 v6, s[4:5], s17, v36
	s_nop 1
	v_addc_co_u32_e64 v7, s[4:5], 0, v37, s[4:5]
	global_load_dword v27, v[6:7], off
	v_add_co_u32_e64 v6, s[4:5], s49, v36
	s_nop 1
	v_addc_co_u32_e64 v7, s[4:5], 0, v37, s[4:5]
	global_load_dword v28, v[6:7], off
	v_add_co_u32_e64 v6, s[4:5], s19, v36
	s_nop 1
	v_addc_co_u32_e64 v7, s[4:5], 0, v37, s[4:5]
	global_load_dword v29, v[6:7], off
	v_add_co_u32_e64 v6, s[4:5], s22, v36
	s_nop 1
	v_addc_co_u32_e64 v7, s[4:5], 0, v37, s[4:5]
	global_load_dword v22, v[6:7], off
	v_add_co_u32_e64 v6, s[4:5], s39, v36
	s_nop 1
	v_addc_co_u32_e64 v7, s[4:5], 0, v37, s[4:5]
	global_load_dword v23, v[6:7], off
	v_add_co_u32_e64 v6, s[4:5], s79, v36
	s_nop 1
	v_addc_co_u32_e64 v7, s[4:5], 0, v37, s[4:5]
	global_load_dword v24, v[6:7], off
	v_add_co_u32_e64 v6, s[4:5], s23, v36
	s_nop 1
	v_addc_co_u32_e64 v7, s[4:5], 0, v37, s[4:5]
	global_load_dword v25, v[6:7], off
	v_add_co_u32_e64 v6, s[4:5], s25, v36
	s_nop 1
	v_addc_co_u32_e64 v7, s[4:5], 0, v37, s[4:5]
	global_load_dword v18, v[6:7], off
	v_add_co_u32_e64 v6, s[4:5], s26, v36
	s_nop 1
	v_addc_co_u32_e64 v7, s[4:5], 0, v37, s[4:5]
	global_load_dword v19, v[6:7], off
	v_add_co_u32_e64 v6, s[4:5], s0, v36
	s_nop 1
	v_addc_co_u32_e64 v7, s[4:5], 0, v37, s[4:5]
	global_load_dword v20, v[6:7], off
	v_add_co_u32_e64 v6, s[4:5], s27, v36
	s_nop 1
	v_addc_co_u32_e64 v7, s[4:5], 0, v37, s[4:5]
	global_load_dword v21, v[6:7], off
	v_add_co_u32_e64 v6, s[4:5], s28, v36
	s_nop 1
	v_addc_co_u32_e64 v7, s[4:5], 0, v37, s[4:5]
	global_load_dword v14, v[6:7], off
	v_add_co_u32_e64 v6, s[4:5], s29, v36
	s_nop 1
	v_addc_co_u32_e64 v7, s[4:5], 0, v37, s[4:5]
	global_load_dword v15, v[6:7], off
	v_add_co_u32_e64 v6, s[4:5], s40, v36
	s_nop 1
	v_addc_co_u32_e64 v7, s[4:5], 0, v37, s[4:5]
	global_load_dword v16, v[6:7], off
	v_add_co_u32_e64 v6, s[4:5], s30, v36
	s_nop 1
	v_addc_co_u32_e64 v7, s[4:5], 0, v37, s[4:5]
	global_load_dword v17, v[6:7], off
	v_add_co_u32_e64 v6, s[4:5], s31, v36
	s_nop 1
	v_addc_co_u32_e64 v7, s[4:5], 0, v37, s[4:5]
	global_load_dword v10, v[6:7], off
	v_add_co_u32_e64 v6, s[4:5], s33, v36
	s_nop 1
	v_addc_co_u32_e64 v7, s[4:5], 0, v37, s[4:5]
	global_load_dword v11, v[6:7], off
	v_add_co_u32_e64 v6, s[4:5], s96, v36
	s_nop 1
	v_addc_co_u32_e64 v7, s[4:5], 0, v37, s[4:5]
	global_load_dword v12, v[6:7], off
	v_add_co_u32_e64 v6, s[4:5], s41, v36
	s_nop 1
	v_addc_co_u32_e64 v7, s[4:5], 0, v37, s[4:5]
	global_load_dword v13, v[6:7], off
	v_add_co_u32_e64 v6, s[4:5], s42, v36
	s_nop 1
	v_addc_co_u32_e64 v7, s[4:5], 0, v37, s[4:5]
	v_add_co_u32_e64 v36, s[4:5], s83, v36
	global_load_dword v6, v[6:7], off
	s_nop 0
	v_addc_co_u32_e64 v37, s[4:5], 0, v37, s[4:5]
	global_load_dword v7, v[36:37], off
	s_waitcnt vmcnt(0)
; #define LAS __attribute__((address_space(3)))
; #define LDS_WAIT() asm volatile("s_waitcnt lgkmcnt(0)" ::: "memory")
; __device__ __forceinline__ unsigned pk2(float lo, float hi) { return pg8::pkbf(lo, hi); }
; __device__ __forceinline__ void transpose_item(const float* W, int K, int N, int NP, bf16* WT, LAS float* scr, int item, int lane, const LAS float* tab, long long* bias, int ldb, const float* kscale = nullptr) {
;     ...
;     for (int i = 0; i < 32; ++i) { if (!okn) wv_[i] = 0.f; if (kscale != nullptr) wv_[i] *= kscale[k0 + 2 * i + (lane >> 5)]; scr[(2 * i + (lane >> 5)) * 33 + (lane & 31)] = wv_[i]; }
;     if (tab != nullptr) {
;         const LAS float* tp = tab + k0 + (lane >> 5);
; #pragma unroll
;         for (int bp = 0; bp < 5; ++bp) { float s = 0.f;
; #pragma unroll
;             for (int i = 0; i < 32; ++i) s += tp[bp * 2048 + 2 * i] * wv_[i];
;             s += __shfl_xor(s, 32);
;             if (lane < 32) atomicAdd((unsigned long long*)(bias + (size_t)bp * ldb + n), (unsigned long long)(long long)(s * 4294967296.f)); }
;     }
;     LDS_WAIT(); asm volatile("" ::: "memory");
;     const int c = lane & 7;
; #pragma unroll
;     for (int j = 0; j < 4; ++j) { const int nn = (lane >> 3) + 8 * j; const LAS float* s = scr + (8 * c) * 33 + nn;
;         v4u o; o.x = pk2(s[0 * 33], s[1 * 33]); o.y = pk2(s[2 * 33], s[3 * 33]); o.z = pk2(s[4 * 33], s[5 * 33]); o.w = pk2(s[6 * 33], s[7 * 33]);
;         *(v4u*)(WT + (size_t)(n0 + nn) * K + k0 + 8 * c) = o; }
;     LDS_WAIT(); asm volatile("" ::: "memory");
	v_cndmask_b32_e32 v35, 0, v35, vcc
	v_cndmask_b32_e32 v30, 0, v30, vcc
	v_cndmask_b32_e32 v31, 0, v31, vcc
	v_cndmask_b32_e32 v26, 0, v26, vcc
	v_cndmask_b32_e32 v27, 0, v27, vcc
	v_cndmask_b32_e32 v22, 0, v22, vcc
	v_cndmask_b32_e32 v23, 0, v23, vcc
	v_cndmask_b32_e32 v18, 0, v18, vcc
	v_cndmask_b32_e32 v19, 0, v19, vcc
	v_cndmask_b32_e32 v14, 0, v14, vcc
	v_cndmask_b32_e32 v15, 0, v15, vcc
	v_cndmask_b32_e32 v10, 0, v10, vcc
	v_cndmask_b32_e32 v11, 0, v11, vcc
	v_add_u32_e32 v37, 0x400, v5
	ds_write2_b32 v37, v30, v31 offset0:140 offset1:206
	v_cndmask_b32_e32 v30, 0, v32, vcc
	v_add_u32_e32 v32, 0x800, v5
	ds_write2_b32 v32, v26, v27 offset0:148 offset1:214
	v_cndmask_b32_e32 v26, 0, v28, vcc
	v_add_u32_e32 v28, 0xc00, v5
	ds_write2_b32 v28, v22, v23 offset0:156 offset1:222
	v_cndmask_b32_e32 v22, 0, v24, vcc
	v_add_u32_e32 v24, 0x1000, v5
	v_cndmask_b32_e32 v36, 0, v38, vcc
	ds_write2_b32 v24, v18, v19 offset0:164 offset1:230
	v_cndmask_b32_e32 v18, 0, v20, vcc
	v_add_u32_e32 v20, 0x1400, v5
	ds_write2_b32 v5, v35, v36 offset1:66
	v_cndmask_b32_e32 v35, 0, v39, vcc
	v_cndmask_b32_e32 v36, 0, v40, vcc
	ds_write2_b32 v20, v14, v15 offset0:172 offset1:238
	v_cndmask_b32_e32 v14, 0, v16, vcc
	v_add_u32_e32 v16, 0x1800, v5
	ds_write2_b32 v5, v35, v36 offset0:132 offset1:198
	v_cndmask_b32_e32 v35, 0, v41, vcc
	v_cndmask_b32_e32 v36, 0, v42, vcc
	v_cndmask_b32_e32 v31, 0, v34, vcc
	v_cndmask_b32_e32 v27, 0, v29, vcc
	v_cndmask_b32_e32 v23, 0, v25, vcc
	v_cndmask_b32_e32 v19, 0, v21, vcc
	v_cndmask_b32_e32 v15, 0, v17, vcc
	ds_write2_b32 v16, v10, v11 offset0:180 offset1:246
	ds_write2_b32 v37, v35, v36 offset0:8 offset1:74
	ds_write2_b32 v32, v30, v31 offset0:16 offset1:82
	ds_write2_b32 v28, v26, v27 offset0:24 offset1:90
	ds_write2_b32 v24, v22, v23 offset0:32 offset1:98
	ds_write2_b32 v20, v18, v19 offset0:40 offset1:106
	ds_write2_b32 v16, v14, v15 offset0:48 offset1:114
	v_add_u32_e32 v30, s10, v9
	v_ashrrev_i32_e32 v31, 31, v30
	v_lshlrev_b64 v[34:35], 14, v[30:31]
	v_add_u32_e32 v9, s38, v9
	s_waitcnt vmcnt(3)
	v_cndmask_b32_e32 v10, 0, v12, vcc
	v_add_u32_e32 v12, 0x1c00, v5
	s_waitcnt vmcnt(2)
	v_cndmask_b32_e32 v11, 0, v13, vcc
	ds_write2_b32 v12, v10, v11 offset0:56 offset1:122
	s_waitcnt vmcnt(1)
	v_cndmask_b32_e32 v6, 0, v6, vcc
	s_waitcnt vmcnt(0)
	v_cndmask_b32_e32 v7, 0, v7, vcc
	ds_write2_b32 v12, v6, v7 offset0:188 offset1:254
	s_waitcnt lgkmcnt(0)
	ds_read2_b32 v[14:15], v4 offset0:33 offset1:41
	ds_read2_b32 v[16:17], v4 offset1:8
	ds_read2_b32 v[18:19], v4 offset0:66 offset1:74
	ds_read2_b32 v[20:21], v4 offset0:99 offset1:107
	ds_read2_b32 v[22:23], v4 offset0:132 offset1:140
	ds_read2_b32 v[24:25], v4 offset0:165 offset1:173
	ds_read2_b32 v[26:27], v4 offset0:198 offset1:206
	ds_read2_b32 v[28:29], v4 offset0:231 offset1:239
	v_lshl_add_u64 v[6:7], s[8:9], 1, v[2:3]
	s_waitcnt lgkmcnt(6)
	v_cvt_pk_bf16_f32 v10, v16, v14
	s_waitcnt lgkmcnt(4)
	v_cvt_pk_bf16_f32 v11, v18, v20
	s_waitcnt lgkmcnt(2)
	v_cvt_pk_bf16_f32 v12, v22, v24
	s_waitcnt lgkmcnt(0)
	v_cvt_pk_bf16_f32 v13, v26, v28
	v_lshl_add_u64 v[34:35], v[6:7], 0, v[34:35]
	v_add_u32_e32 v14, 8, v30
	global_store_dwordx4 v[34:35], v[10:13], off
	v_add_u32_e32 v34, 16, v30
	v_ashrrev_i32_e32 v35, 31, v34
	v_cvt_pk_bf16_f32 v10, v17, v15
	v_ashrrev_i32_e32 v15, 31, v14
	v_lshlrev_b64 v[14:15], 14, v[14:15]
	v_cvt_pk_bf16_f32 v11, v19, v21
	v_cvt_pk_bf16_f32 v12, v23, v25
	v_cvt_pk_bf16_f32 v13, v27, v29
	v_lshl_add_u64 v[14:15], v[6:7], 0, v[14:15]
	global_store_dwordx4 v[14:15], v[10:13], off
	ds_read2_b32 v[14:15], v4 offset0:49 offset1:57
	ds_read2_b32 v[16:17], v4 offset0:16 offset1:24
	ds_read2_b32 v[18:19], v4 offset0:82 offset1:90
	ds_read2_b32 v[20:21], v4 offset0:115 offset1:123
	ds_read2_b32 v[22:23], v4 offset0:148 offset1:156
	ds_read2_b32 v[24:25], v4 offset0:181 offset1:189
	ds_read2_b32 v[26:27], v4 offset0:214 offset1:222
	ds_read2_b32 v[28:29], v4 offset0:247 offset1:255
	v_lshlrev_b64 v[34:35], 14, v[34:35]
	s_waitcnt lgkmcnt(6)
	v_cvt_pk_bf16_f32 v10, v16, v14
	s_waitcnt lgkmcnt(4)
	v_cvt_pk_bf16_f32 v11, v18, v20
	s_waitcnt lgkmcnt(2)
	v_cvt_pk_bf16_f32 v12, v22, v24
	s_waitcnt lgkmcnt(0)
	v_cvt_pk_bf16_f32 v13, v26, v28
	v_lshl_add_u64 v[34:35], v[6:7], 0, v[34:35]
	v_add_u32_e32 v14, 24, v30
	global_store_dwordx4 v[34:35], v[10:13], off
	s_nop 1
	v_cvt_pk_bf16_f32 v10, v17, v15
	v_ashrrev_i32_e32 v15, 31, v14
	v_lshlrev_b64 v[14:15], 14, v[14:15]
	v_cvt_pk_bf16_f32 v11, v19, v21
	v_cvt_pk_bf16_f32 v12, v23, v25
	v_cvt_pk_bf16_f32 v13, v27, v29
	v_lshl_add_u64 v[6:7], v[6:7], 0, v[14:15]
	global_store_dwordx4 v[6:7], v[10:13], off
	s_waitcnt lgkmcnt(0)
	s_cbranch_scc1 .LBB0_1368
